# context attention epilogue: the 16 subln-gain loads hoisted ahead of the stores (same change as the latent epilogue)
# baseline (speedup 1.0000x reference)
; __device__ __forceinline__ void attn_unit(LAS unsigned char* lds, const Args& A, int b, int h, int qrow0, int nkt) {
;     ...
;     if (map == 0) {
;         float ss = 0.f;
; #pragma unroll
;         for (int i = 0; i < 4; ++i)
; #pragma unroll
;             for (int r = 0; r < 16; ++r) { const float o = O[i][r] * inv - A.lam * ex[(i * 16 + r) * 64 + lane]; O[i][r] = o; ss += o * o; }
.LBB0_688:
	s_andn2_b64 vcc, exec, s[6:7]
	s_waitcnt lgkmcnt(0)
	s_barrier
	s_cbranch_vccnz .LBB0_690
	ds_read2st64_b32 v[66:67], v68 offset1:1
	v_mov_b32_e32 v166, v48
	v_readlane_b32 s0, v253, 16
	v_readlane_b32 s1, v253, 17
	s_lshl_b32 s42, s12, 8
	s_waitcnt lgkmcnt(0)
	v_mov_b32_e32 v65, v66
	v_pk_mul_f32 v[70:71], v[166:167], v[64:65]
	v_mov_b32_e32 v166, v49
	v_mov_b32_e32 v65, v67
	v_pk_mul_f32 v[66:67], v[166:167], v[64:65]
	v_mov_b32_e32 v166, v50
	v_sub_f32_e32 v49, v66, v67
	ds_read2st64_b32 v[66:67], v68 offset0:2 offset1:3
	v_sub_f32_e32 v48, v70, v71
	s_waitcnt lgkmcnt(0)
	v_mov_b32_e32 v65, v66
	v_pk_mul_f32 v[70:71], v[166:167], v[64:65]
	v_mov_b32_e32 v166, v51
	v_mov_b32_e32 v65, v67
	v_pk_mul_f32 v[66:67], v[166:167], v[64:65]
	v_mov_b32_e32 v166, v52
	v_sub_f32_e32 v51, v66, v67
	ds_read2st64_b32 v[66:67], v68 offset0:4 offset1:5
	v_sub_f32_e32 v50, v70, v71
	s_waitcnt lgkmcnt(0)
	v_mov_b32_e32 v65, v66
	v_pk_mul_f32 v[70:71], v[166:167], v[64:65]
	v_mov_b32_e32 v166, v53
	v_mov_b32_e32 v65, v67
	v_pk_mul_f32 v[66:67], v[166:167], v[64:65]
	v_mov_b32_e32 v166, v54
	v_sub_f32_e32 v53, v66, v67
	ds_read2st64_b32 v[66:67], v68 offset0:6 offset1:7
	v_sub_f32_e32 v52, v70, v71
	s_waitcnt lgkmcnt(0)
	v_mov_b32_e32 v65, v66
	v_pk_mul_f32 v[70:71], v[166:167], v[64:65]
	v_mov_b32_e32 v166, v55
	v_mov_b32_e32 v65, v67
	v_pk_mul_f32 v[66:67], v[166:167], v[64:65]
	v_mov_b32_e32 v166, v56
	v_sub_f32_e32 v55, v66, v67
	ds_read2st64_b32 v[66:67], v68 offset0:8 offset1:9
	v_sub_f32_e32 v54, v70, v71
	s_waitcnt lgkmcnt(0)
	v_mov_b32_e32 v65, v66
	v_pk_mul_f32 v[70:71], v[166:167], v[64:65]
	v_mov_b32_e32 v166, v57
	v_mov_b32_e32 v65, v67
	v_pk_mul_f32 v[66:67], v[166:167], v[64:65]
	v_mov_b32_e32 v166, v58
	v_sub_f32_e32 v57, v66, v67
	ds_read2st64_b32 v[66:67], v68 offset0:10 offset1:11
	v_sub_f32_e32 v56, v70, v71
	s_waitcnt lgkmcnt(0)
	v_mov_b32_e32 v65, v66
	v_pk_mul_f32 v[70:71], v[166:167], v[64:65]
	v_mov_b32_e32 v166, v59
	v_mov_b32_e32 v65, v67
	v_pk_mul_f32 v[66:67], v[166:167], v[64:65]
	v_mov_b32_e32 v166, v60
	v_sub_f32_e32 v59, v66, v67
	ds_read2st64_b32 v[66:67], v68 offset0:12 offset1:13
	v_sub_f32_e32 v58, v70, v71
	s_waitcnt lgkmcnt(0)
	v_mov_b32_e32 v65, v66
	v_pk_mul_f32 v[70:71], v[166:167], v[64:65]
	v_mov_b32_e32 v166, v61
	v_mov_b32_e32 v65, v67
	v_pk_mul_f32 v[66:67], v[166:167], v[64:65]
	v_mov_b32_e32 v166, v62
	v_sub_f32_e32 v61, v66, v67
	ds_read2st64_b32 v[66:67], v68 offset0:14 offset1:15
	v_sub_f32_e32 v60, v70, v71
	s_waitcnt lgkmcnt(0)
	v_mov_b32_e32 v65, v66
	v_pk_mul_f32 v[70:71], v[166:167], v[64:65]
	v_mov_b32_e32 v166, v63
	v_mov_b32_e32 v65, v67
	v_pk_mul_f32 v[66:67], v[166:167], v[64:65]
	v_mov_b32_e32 v166, v32
	v_sub_f32_e32 v63, v66, v67
	ds_read2st64_b32 v[66:67], v68 offset0:16 offset1:17
	v_sub_f32_e32 v62, v70, v71
	s_waitcnt lgkmcnt(0)
	v_mov_b32_e32 v65, v66
	v_pk_mul_f32 v[70:71], v[166:167], v[64:65]
	v_mov_b32_e32 v166, v33
	v_sub_f32_e32 v66, v70, v71
	ds_read2st64_b32 v[70:71], v68 offset0:18 offset1:19
	v_mov_b32_e32 v65, v67
	v_pk_mul_f32 v[32:33], v[166:167], v[64:65]
	v_mov_b32_e32 v166, v34
	v_sub_f32_e32 v32, v32, v33
	s_waitcnt lgkmcnt(0)
	v_mov_b32_e32 v65, v70
	v_pk_mul_f32 v[72:73], v[166:167], v[64:65]
	v_mov_b32_e32 v166, v35
	v_mov_b32_e32 v65, v71
	v_pk_mul_f32 v[70:71], v[166:167], v[64:65]
	v_mov_b32_e32 v166, v36
	v_sub_f32_e32 v33, v70, v71
	ds_read2st64_b32 v[70:71], v68 offset0:20 offset1:21
	v_sub_f32_e32 v34, v72, v73
	s_waitcnt lgkmcnt(0)
	v_mov_b32_e32 v65, v70
	v_pk_mul_f32 v[72:73], v[166:167], v[64:65]
	v_mov_b32_e32 v166, v37
	v_mov_b32_e32 v65, v71
	v_pk_mul_f32 v[70:71], v[166:167], v[64:65]
	v_mov_b32_e32 v166, v38
	v_sub_f32_e32 v35, v70, v71
	ds_read2st64_b32 v[70:71], v68 offset0:22 offset1:23
	v_sub_f32_e32 v36, v72, v73
	s_waitcnt lgkmcnt(0)
	v_mov_b32_e32 v65, v70
	v_pk_mul_f32 v[72:73], v[166:167], v[64:65]
	v_mov_b32_e32 v65, v71
	ds_read2st64_b32 v[70:71], v68 offset0:24 offset1:25
	v_mov_b32_e32 v166, v39
	v_pk_mul_f32 v[38:39], v[166:167], v[64:65]
	v_mov_b32_e32 v166, v40
	v_sub_f32_e32 v67, v72, v73
	s_waitcnt lgkmcnt(0)
	v_mov_b32_e32 v65, v70
	v_pk_mul_f32 v[72:73], v[166:167], v[64:65]
	v_mov_b32_e32 v65, v71
	ds_read2st64_b32 v[70:71], v68 offset0:26 offset1:27
	v_mov_b32_e32 v166, v41
	v_pk_mul_f32 v[40:41], v[166:167], v[64:65]
	v_mov_b32_e32 v166, v42
	v_sub_f32_e32 v37, v40, v41
	s_waitcnt lgkmcnt(0)
	v_mov_b32_e32 v65, v70
	v_pk_mul_f32 v[40:41], v[166:167], v[64:65]
	v_mov_b32_e32 v65, v71
	ds_read2st64_b32 v[70:71], v68 offset0:28 offset1:29
	v_mov_b32_e32 v166, v43
	v_pk_mul_f32 v[42:43], v[166:167], v[64:65]
	v_mov_b32_e32 v166, v44
	v_sub_f32_e32 v41, v40, v41
	s_waitcnt lgkmcnt(0)
	v_mov_b32_e32 v65, v70
	v_sub_f32_e32 v40, v42, v43
	v_pk_mul_f32 v[42:43], v[166:167], v[64:65]
	v_mov_b32_e32 v65, v71
	ds_read2st64_b32 v[70:71], v68 offset0:30 offset1:31
	v_mov_b32_e32 v166, v45
	v_pk_mul_f32 v[44:45], v[166:167], v[64:65]
	v_mov_b32_e32 v166, v46
	v_sub_f32_e32 v43, v42, v43
	s_waitcnt lgkmcnt(0)
	v_mov_b32_e32 v65, v70
	v_sub_f32_e32 v42, v44, v45
	v_pk_mul_f32 v[44:45], v[166:167], v[64:65]
	v_mov_b32_e32 v166, v47
	v_mov_b32_e32 v65, v71
	v_pk_mul_f32 v[46:47], v[166:167], v[64:65]
	v_sub_f32_e32 v45, v44, v45
	v_sub_f32_e32 v44, v46, v47
	ds_read2st64_b32 v[46:47], v68 offset0:32 offset1:33
	v_mov_b32_e32 v166, v16
	v_sub_f32_e32 v39, v38, v39
	v_sub_f32_e32 v38, v72, v73
	s_waitcnt lgkmcnt(0)
	v_mov_b32_e32 v65, v46
	v_pk_mul_f32 v[70:71], v[166:167], v[64:65]
	v_mov_b32_e32 v166, v17
	v_sub_f32_e32 v46, v70, v71
	ds_read2st64_b32 v[70:71], v68 offset0:34 offset1:35
	v_mov_b32_e32 v65, v47
	v_pk_mul_f32 v[16:17], v[166:167], v[64:65]
	v_mov_b32_e32 v166, v18
	v_sub_f32_e32 v16, v16, v17
	s_waitcnt lgkmcnt(0)
; __device__ __forceinline__ void attn_unit(LAS unsigned char* lds, const Args& A, int b, int h, int qrow0, int nkt) {
;     ...
;             for (int r = 0; r < 16; ++r) { const float o = O[i][r] * inv - A.lam * ex[(i * 16 + r) * 64 + lane]; O[i][r] = o; ss += o * o; }
;         ss += __shfl_xor(ss, 32);
	v_mov_b32_e32 v65, v70
	v_pk_mul_f32 v[72:73], v[166:167], v[64:65]
	v_mov_b32_e32 v166, v19
	v_mov_b32_e32 v65, v71
	v_pk_mul_f32 v[70:71], v[166:167], v[64:65]
	v_mov_b32_e32 v166, v20
	v_sub_f32_e32 v17, v70, v71
	ds_read2st64_b32 v[70:71], v68 offset0:36 offset1:37
	v_sub_f32_e32 v18, v72, v73
	s_waitcnt lgkmcnt(0)
	v_mov_b32_e32 v65, v70
	v_pk_mul_f32 v[72:73], v[166:167], v[64:65]
	v_mov_b32_e32 v166, v21
	v_mov_b32_e32 v65, v71
	v_pk_mul_f32 v[70:71], v[166:167], v[64:65]
	v_mov_b32_e32 v166, v22
	v_sub_f32_e32 v19, v70, v71
	ds_read2st64_b32 v[70:71], v68 offset0:38 offset1:39
	v_sub_f32_e32 v20, v72, v73
	s_waitcnt lgkmcnt(0)
	v_mov_b32_e32 v65, v70
	v_pk_mul_f32 v[72:73], v[166:167], v[64:65]
	v_mov_b32_e32 v65, v71
	ds_read2st64_b32 v[70:71], v68 offset0:40 offset1:41
	v_mov_b32_e32 v166, v23
	v_pk_mul_f32 v[22:23], v[166:167], v[64:65]
	v_mov_b32_e32 v166, v24
	v_sub_f32_e32 v47, v72, v73
	s_waitcnt lgkmcnt(0)
	v_mov_b32_e32 v65, v70
	v_pk_mul_f32 v[72:73], v[166:167], v[64:65]
	v_mov_b32_e32 v65, v71
	ds_read2st64_b32 v[70:71], v68 offset0:42 offset1:43
	v_mov_b32_e32 v166, v25
	v_pk_mul_f32 v[24:25], v[166:167], v[64:65]
	v_mov_b32_e32 v166, v26
	v_sub_f32_e32 v21, v24, v25
	s_waitcnt lgkmcnt(0)
	v_mov_b32_e32 v65, v70
	v_pk_mul_f32 v[24:25], v[166:167], v[64:65]
	v_mov_b32_e32 v65, v71
	ds_read2st64_b32 v[70:71], v68 offset0:44 offset1:45
	v_mov_b32_e32 v166, v27
	v_pk_mul_f32 v[26:27], v[166:167], v[64:65]
	v_mov_b32_e32 v166, v28
	v_sub_f32_e32 v25, v24, v25
	s_waitcnt lgkmcnt(0)
	v_mov_b32_e32 v65, v70
	v_sub_f32_e32 v24, v26, v27
	v_pk_mul_f32 v[26:27], v[166:167], v[64:65]
	v_mov_b32_e32 v166, v29
	v_mov_b32_e32 v65, v71
	v_pk_mul_f32 v[28:29], v[166:167], v[64:65]
	v_sub_f32_e32 v27, v26, v27
	v_sub_f32_e32 v26, v28, v29
	ds_read2st64_b32 v[28:29], v68 offset0:46 offset1:47
	v_mov_b32_e32 v166, v30
	v_sub_f32_e32 v23, v22, v23
	v_sub_f32_e32 v22, v72, v73
	s_waitcnt lgkmcnt(0)
	v_mov_b32_e32 v65, v28
	v_pk_mul_f32 v[70:71], v[166:167], v[64:65]
	v_mov_b32_e32 v166, v31
	ds_read2st64_b32 v[30:31], v68 offset0:48 offset1:49
	v_mov_b32_e32 v65, v29
	v_pk_mul_f32 v[28:29], v[166:167], v[64:65]
	v_mov_b32_e32 v166, v0
	v_sub_f32_e32 v69, v70, v71
	s_waitcnt lgkmcnt(0)
	v_mov_b32_e32 v65, v30
	v_pk_mul_f32 v[70:71], v[166:167], v[64:65]
	v_mov_b32_e32 v166, v1
	v_mov_b32_e32 v65, v31
	v_pk_mul_f32 v[0:1], v[166:167], v[64:65]
	v_sub_f32_e32 v29, v28, v29
	v_sub_f32_e32 v28, v0, v1
	ds_read2st64_b32 v[0:1], v68 offset0:50 offset1:51
	v_mov_b32_e32 v166, v2
	v_sub_f32_e32 v30, v70, v71
	s_waitcnt lgkmcnt(0)
	v_mov_b32_e32 v65, v0
	v_pk_mul_f32 v[70:71], v[166:167], v[64:65]
	v_mov_b32_e32 v166, v3
	v_mov_b32_e32 v65, v1
	v_pk_mul_f32 v[0:1], v[166:167], v[64:65]
	v_mov_b32_e32 v166, v4
	v_sub_f32_e32 v31, v0, v1
	ds_read2st64_b32 v[0:1], v68 offset0:52 offset1:53
	v_sub_f32_e32 v70, v70, v71
	s_waitcnt lgkmcnt(0)
	v_mov_b32_e32 v65, v0
	v_pk_mul_f32 v[2:3], v[166:167], v[64:65]
	v_mov_b32_e32 v166, v5
	v_mov_b32_e32 v65, v1
	v_pk_mul_f32 v[0:1], v[166:167], v[64:65]
	v_mov_b32_e32 v166, v6
	v_sub_f32_e32 v71, v0, v1
	ds_read2st64_b32 v[0:1], v68 offset0:54 offset1:55
	v_sub_f32_e32 v72, v2, v3
	s_waitcnt lgkmcnt(0)
	v_mov_b32_e32 v65, v0
	v_pk_mul_f32 v[2:3], v[166:167], v[64:65]
	v_mov_b32_e32 v166, v7
	v_mov_b32_e32 v65, v1
	v_pk_mul_f32 v[0:1], v[166:167], v[64:65]
	v_mov_b32_e32 v166, v8
	v_mul_f32_e32 v8, v48, v48
	v_fmac_f32_e32 v8, v49, v49
	v_fmac_f32_e32 v8, v50, v50
	v_fmac_f32_e32 v8, v51, v51
	v_fmac_f32_e32 v8, v52, v52
	v_fmac_f32_e32 v8, v53, v53
	v_fmac_f32_e32 v8, v54, v54
	v_fmac_f32_e32 v8, v55, v55
	v_fmac_f32_e32 v8, v56, v56
	v_fmac_f32_e32 v8, v57, v57
	v_fmac_f32_e32 v8, v58, v58
	v_fmac_f32_e32 v8, v59, v59
	v_fmac_f32_e32 v8, v60, v60
	v_fmac_f32_e32 v8, v61, v61
	v_fmac_f32_e32 v8, v62, v62
	v_fmac_f32_e32 v8, v63, v63
	v_fmac_f32_e32 v8, v66, v66
	v_fmac_f32_e32 v8, v32, v32
	v_fmac_f32_e32 v8, v34, v34
	v_fmac_f32_e32 v8, v33, v33
	v_fmac_f32_e32 v8, v36, v36
	v_fmac_f32_e32 v8, v35, v35
	v_fmac_f32_e32 v8, v67, v67
	v_fmac_f32_e32 v8, v39, v39
	v_fmac_f32_e32 v8, v38, v38
	v_fmac_f32_e32 v8, v37, v37
	v_fmac_f32_e32 v8, v41, v41
	v_fmac_f32_e32 v8, v40, v40
	v_fmac_f32_e32 v8, v43, v43
	v_fmac_f32_e32 v8, v42, v42
	v_fmac_f32_e32 v8, v45, v45
	v_fmac_f32_e32 v8, v44, v44
	v_fmac_f32_e32 v8, v46, v46
	v_fmac_f32_e32 v8, v16, v16
	v_fmac_f32_e32 v8, v18, v18
	v_fmac_f32_e32 v8, v17, v17
	v_sub_f32_e32 v75, v0, v1
	ds_read2st64_b32 v[0:1], v68 offset0:56 offset1:57
	v_fmac_f32_e32 v8, v20, v20
	v_fmac_f32_e32 v8, v19, v19
	v_fmac_f32_e32 v8, v47, v47
	v_fmac_f32_e32 v8, v23, v23
	v_fmac_f32_e32 v8, v22, v22
	s_waitcnt lgkmcnt(0)
	v_mov_b32_e32 v65, v0
	v_fmac_f32_e32 v8, v21, v21
	v_sub_f32_e32 v76, v2, v3
	v_pk_mul_f32 v[2:3], v[166:167], v[64:65]
	v_mov_b32_e32 v166, v9
	v_mov_b32_e32 v65, v1
	v_fmac_f32_e32 v8, v25, v25
	v_pk_mul_f32 v[0:1], v[166:167], v[64:65]
	v_fmac_f32_e32 v8, v24, v24
	v_sub_f32_e32 v73, v0, v1
	ds_read2st64_b32 v[0:1], v68 offset0:58 offset1:59
	v_fmac_f32_e32 v8, v27, v27
	v_fmac_f32_e32 v8, v26, v26
	v_fmac_f32_e32 v8, v69, v69
	v_fmac_f32_e32 v8, v29, v29
	v_fmac_f32_e32 v8, v30, v30
	v_mov_b32_e32 v166, v10
	s_waitcnt lgkmcnt(0)
	v_mov_b32_e32 v65, v0
	v_fmac_f32_e32 v8, v28, v28
	v_sub_f32_e32 v74, v2, v3
	v_pk_mul_f32 v[2:3], v[166:167], v[64:65]
	v_mov_b32_e32 v166, v11
	v_mov_b32_e32 v65, v1
	v_fmac_f32_e32 v8, v70, v70
	v_pk_mul_f32 v[0:1], v[166:167], v[64:65]
	v_fmac_f32_e32 v8, v31, v31
	v_sub_f32_e32 v10, v0, v1
	ds_read2st64_b32 v[0:1], v68 offset0:60 offset1:61
	v_fmac_f32_e32 v8, v72, v72
	v_fmac_f32_e32 v8, v71, v71
	v_sub_f32_e32 v77, v2, v3
	ds_read2st64_b32 v[2:3], v68 offset0:62 offset1:63
	v_fmac_f32_e32 v8, v76, v76
	v_fmac_f32_e32 v8, v75, v75
	v_fmac_f32_e32 v8, v74, v74
	s_waitcnt lgkmcnt(1)
; __device__ __forceinline__ void attn_unit(LAS unsigned char* lds, const Args& A, int b, int h, int qrow0, int nkt) {
;     ...
;         ss += __shfl_xor(ss, 32);
;         const float rstd = __builtin_amdgcn_rsqf(ss * (1.f / 128.f) + EPSV) * A.omli;
;         bf16_t* dst = A.MIXA + (size_t)(qrow0 + qg * 32 + r32) * DM + h * 128 + 4 * hi;
; #pragma unroll
;         for (int i = 0; i < 4; ++i)
; #pragma unroll
;             for (int rq = 0; rq < 4; ++rq) {
;                 const int d0 = 32 * i + 8 * rq;
;                 const f32x4 gg = *(const f32x4*)(A.subln + d0 + 4 * hi);
	v_pk_mul_f32 v[0:1], v[168:169], v[0:1]
	v_fmac_f32_e32 v8, v73, v73
	v_pk_fma_f32 v[4:5], v[12:13], v[64:65], v[0:1] op_sel_hi:[1,0,1] neg_lo:[0,0,1] neg_hi:[0,0,1]
	v_fmac_f32_e32 v8, v77, v77
	v_pk_mul_f32 v[0:1], v[4:5], v[4:5]
	s_waitcnt lgkmcnt(0)
	v_pk_mul_f32 v[2:3], v[168:169], v[2:3]
	v_fmac_f32_e32 v8, v10, v10
	v_pk_fma_f32 v[6:7], v[14:15], v[64:65], v[2:3] op_sel_hi:[1,0,1] neg_lo:[0,0,1] neg_hi:[0,0,1]
	v_add_f32_e32 v0, v8, v0
	v_pk_mul_f32 v[2:3], v[6:7], v[6:7]
	v_add_f32_e32 v0, v0, v1
	v_add_f32_e32 v0, v0, v2
	v_add_f32_e32 v0, v0, v3
	ds_bpermute_b32 v1, v214, v0
	s_waitcnt lgkmcnt(0)
	v_add_f32_e32 v0, v0, v1
	v_fmamk_f32 v0, v0, 0x3c000000, v193
	v_rsq_f32_e32 v0, v0
	s_nop 0
	v_mul_f32_e32 v11, v215, v0
	v_lshlrev_b64 v[0:1], 11, v[160:161]
	v_lshl_add_u64 v[0:1], s[0:1], 0, v[0:1]
	v_lshl_add_u64 v[0:1], v[0:1], 0, s[42:43]
	v_lshlrev_b32_e32 v160, 3, v216
	v_lshl_add_u64 v[8:9], v[0:1], 0, v[160:161]
	global_load_dwordx4 v[80:83], v170, s[4:5]
	global_load_dwordx4 v[84:87], v170, s[4:5] offset:32
	global_load_dwordx4 v[88:91], v170, s[4:5] offset:64
	global_load_dwordx4 v[92:95], v170, s[4:5] offset:96
	global_load_dwordx4 v[96:99], v170, s[4:5] offset:128
	global_load_dwordx4 v[100:103], v170, s[4:5] offset:160
	global_load_dwordx4 v[104:107], v170, s[4:5] offset:192
	global_load_dwordx4 v[108:111], v170, s[4:5] offset:224
	global_load_dwordx4 v[112:115], v170, s[4:5] offset:256
	global_load_dwordx4 v[116:119], v170, s[4:5] offset:288
	global_load_dwordx4 v[120:123], v170, s[4:5] offset:320
	global_load_dwordx4 v[124:127], v170, s[4:5] offset:352
	global_load_dwordx4 v[128:131], v170, s[4:5] offset:384
	global_load_dwordx4 v[132:135], v170, s[4:5] offset:416
	global_load_dwordx4 v[136:139], v170, s[4:5] offset:448
	global_load_dwordx4 v[140:143], v170, s[4:5] offset:480
	s_waitcnt vmcnt(0)
; __device__ __forceinline__ u32x2 pack4(f32x4 v) { u32x2 w; w.x = cvt_pk_bf16(v[0], v[1]); w.y = cvt_pk_bf16(v[2], v[3]); return w; }
; __device__ __forceinline__ void attn_unit(LAS unsigned char* lds, const Args& A, int b, int h, int qrow0, int nkt) {
;     ...
;                 const int d0 = 32 * i + 8 * rq;
;                 const f32x4 gg = *(const f32x4*)(A.subln + d0 + 4 * hi);
;                 f32x4 v = {O[i][4 * rq] * rstd * gg[0], O[i][4 * rq + 1] * rstd * gg[1], O[i][4 * rq + 2] * rstd * gg[2], O[i][4 * rq + 3] * rstd * gg[3]};
;                 *(u32x2*)(dst + d0) = pack4(v);
	v_mul_f32_e32 v12, v48, v11
	v_mul_f32_e32 v10, v10, v11
	v_mul_f32_e32 v4, v4, v11
	v_mul_f32_e32 v0, v80, v12
	v_mul_f32_e32 v12, v49, v11
	v_mul_f32_e32 v1, v81, v12
	v_mul_f32_e32 v12, v50, v11
	v_mul_f32_e32 v2, v82, v12
	v_mul_f32_e32 v12, v51, v11
	v_mul_f32_e32 v3, v83, v12
	v_cvt_pk_bf16_f32 v0, v0, v1
	v_cvt_pk_bf16_f32 v1, v2, v3
	global_store_dwordx2 v[8:9], v[0:1], off
	v_mul_f32_e32 v12, v52, v11
	v_mul_f32_e32 v144, v84, v12
	v_mul_f32_e32 v12, v53, v11
	v_mul_f32_e32 v145, v85, v12
	v_mul_f32_e32 v12, v54, v11
	v_mul_f32_e32 v146, v86, v12
	v_mul_f32_e32 v12, v55, v11
	v_mul_f32_e32 v147, v87, v12
	v_cvt_pk_bf16_f32 v144, v144, v145
	v_cvt_pk_bf16_f32 v145, v146, v147
	global_store_dwordx2 v[8:9], v[144:145], off offset:16
	v_mul_f32_e32 v12, v56, v11
	v_mul_f32_e32 v0, v88, v12
	v_mul_f32_e32 v12, v57, v11
	v_mul_f32_e32 v1, v89, v12
	v_mul_f32_e32 v12, v58, v11
	v_mul_f32_e32 v2, v90, v12
	v_mul_f32_e32 v12, v59, v11
	v_mul_f32_e32 v3, v91, v12
	v_cvt_pk_bf16_f32 v0, v0, v1
	v_cvt_pk_bf16_f32 v1, v2, v3
	global_store_dwordx2 v[8:9], v[0:1], off offset:32
	v_mul_f32_e32 v12, v60, v11
	v_mul_f32_e32 v144, v92, v12
	v_mul_f32_e32 v12, v61, v11
	v_mul_f32_e32 v145, v93, v12
	v_mul_f32_e32 v12, v62, v11
	v_mul_f32_e32 v146, v94, v12
	v_mul_f32_e32 v12, v63, v11
	v_mul_f32_e32 v147, v95, v12
	v_cvt_pk_bf16_f32 v144, v144, v145
	v_cvt_pk_bf16_f32 v145, v146, v147
	global_store_dwordx2 v[8:9], v[144:145], off offset:48
	v_mul_f32_e32 v12, v66, v11
	v_mul_f32_e32 v0, v96, v12
	v_mul_f32_e32 v12, v32, v11
	v_mul_f32_e32 v1, v97, v12
	v_mul_f32_e32 v12, v34, v11
	v_mul_f32_e32 v2, v98, v12
	v_mul_f32_e32 v12, v33, v11
	v_mul_f32_e32 v3, v99, v12
	v_cvt_pk_bf16_f32 v0, v0, v1
	v_cvt_pk_bf16_f32 v1, v2, v3
	global_store_dwordx2 v[8:9], v[0:1], off offset:64
	v_mul_f32_e32 v12, v36, v11
	v_mul_f32_e32 v144, v100, v12
	v_mul_f32_e32 v12, v35, v11
	v_mul_f32_e32 v145, v101, v12
	v_mul_f32_e32 v12, v67, v11
	v_mul_f32_e32 v146, v102, v12
	v_mul_f32_e32 v12, v39, v11
	v_mul_f32_e32 v147, v103, v12
	v_cvt_pk_bf16_f32 v144, v144, v145
	v_cvt_pk_bf16_f32 v145, v146, v147
	global_store_dwordx2 v[8:9], v[144:145], off offset:80
	v_mul_f32_e32 v12, v38, v11
	v_mul_f32_e32 v0, v104, v12
	v_mul_f32_e32 v12, v37, v11
	v_mul_f32_e32 v1, v105, v12
	v_mul_f32_e32 v12, v41, v11
	v_mul_f32_e32 v2, v106, v12
	v_mul_f32_e32 v12, v40, v11
	v_mul_f32_e32 v3, v107, v12
	v_cvt_pk_bf16_f32 v0, v0, v1
	v_cvt_pk_bf16_f32 v1, v2, v3
	global_store_dwordx2 v[8:9], v[0:1], off offset:96
	v_mul_f32_e32 v12, v43, v11
	v_mul_f32_e32 v144, v108, v12
	v_mul_f32_e32 v12, v42, v11
	v_mul_f32_e32 v145, v109, v12
	v_mul_f32_e32 v12, v45, v11
	v_mul_f32_e32 v146, v110, v12
	v_mul_f32_e32 v12, v44, v11
	v_mul_f32_e32 v147, v111, v12
	v_cvt_pk_bf16_f32 v144, v144, v145
	v_cvt_pk_bf16_f32 v145, v146, v147
	global_store_dwordx2 v[8:9], v[144:145], off offset:112
	v_mul_f32_e32 v12, v46, v11
	v_mul_f32_e32 v0, v112, v12
	v_mul_f32_e32 v12, v16, v11
	v_mul_f32_e32 v1, v113, v12
	v_mul_f32_e32 v12, v18, v11
	v_mul_f32_e32 v2, v114, v12
	v_mul_f32_e32 v12, v17, v11
	v_mul_f32_e32 v3, v115, v12
	v_cvt_pk_bf16_f32 v0, v0, v1
	v_cvt_pk_bf16_f32 v1, v2, v3
	global_store_dwordx2 v[8:9], v[0:1], off offset:128
	v_mul_f32_e32 v12, v20, v11
	v_mul_f32_e32 v144, v116, v12
	v_mul_f32_e32 v12, v19, v11
	v_mul_f32_e32 v145, v117, v12
	v_mul_f32_e32 v12, v47, v11
	v_mul_f32_e32 v146, v118, v12
	v_mul_f32_e32 v12, v23, v11
	v_mul_f32_e32 v147, v119, v12
	v_cvt_pk_bf16_f32 v144, v144, v145
	v_cvt_pk_bf16_f32 v145, v146, v147
	global_store_dwordx2 v[8:9], v[144:145], off offset:144
	v_mul_f32_e32 v12, v22, v11
	v_mul_f32_e32 v0, v120, v12
	v_mul_f32_e32 v12, v21, v11
	v_mul_f32_e32 v1, v121, v12
	v_mul_f32_e32 v12, v25, v11
	v_mul_f32_e32 v2, v122, v12
	v_mul_f32_e32 v12, v24, v11
	v_mul_f32_e32 v3, v123, v12
	v_cvt_pk_bf16_f32 v0, v0, v1
	v_cvt_pk_bf16_f32 v1, v2, v3
	global_store_dwordx2 v[8:9], v[0:1], off offset:160
	v_mul_f32_e32 v12, v27, v11
	v_mul_f32_e32 v144, v124, v12
	v_mul_f32_e32 v12, v26, v11
	v_mul_f32_e32 v145, v125, v12
	v_mul_f32_e32 v12, v69, v11
	v_mul_f32_e32 v146, v126, v12
	v_mul_f32_e32 v12, v29, v11
	v_mul_f32_e32 v147, v127, v12
	v_cvt_pk_bf16_f32 v144, v144, v145
	v_cvt_pk_bf16_f32 v145, v146, v147
	global_store_dwordx2 v[8:9], v[144:145], off offset:176
	v_mul_f32_e32 v12, v30, v11
	v_mul_f32_e32 v0, v128, v12
	v_mul_f32_e32 v12, v28, v11
	v_mul_f32_e32 v1, v129, v12
	v_mul_f32_e32 v12, v70, v11
	v_mul_f32_e32 v2, v130, v12
	v_mul_f32_e32 v12, v31, v11
	v_mul_f32_e32 v3, v131, v12
	v_cvt_pk_bf16_f32 v0, v0, v1
	v_cvt_pk_bf16_f32 v1, v2, v3
	global_store_dwordx2 v[8:9], v[0:1], off offset:192
	v_mul_f32_e32 v12, v72, v11
	v_mul_f32_e32 v144, v132, v12
	v_mul_f32_e32 v12, v71, v11
	v_mul_f32_e32 v145, v133, v12
	v_mul_f32_e32 v12, v76, v11
	v_mul_f32_e32 v146, v134, v12
	v_mul_f32_e32 v12, v75, v11
	v_mul_f32_e32 v147, v135, v12
	v_cvt_pk_bf16_f32 v144, v144, v145
	v_cvt_pk_bf16_f32 v145, v146, v147
	global_store_dwordx2 v[8:9], v[144:145], off offset:208
	v_mul_f32_e32 v12, v74, v11
	v_mul_f32_e32 v0, v136, v12
	v_mul_f32_e32 v12, v73, v11
	v_mul_f32_e32 v1, v137, v12
	v_mul_f32_e32 v12, v77, v11
	v_mul_f32_e32 v2, v138, v12
	v_mul_f32_e32 v3, v139, v10
	v_cvt_pk_bf16_f32 v0, v0, v1
	v_cvt_pk_bf16_f32 v1, v2, v3
	global_store_dwordx2 v[8:9], v[0:1], off offset:224
	v_mul_f32_e32 v144, v140, v4
	v_mul_f32_e32 v4, v5, v11
	v_mul_f32_e32 v145, v141, v4
	v_mul_f32_e32 v4, v6, v11
	v_mul_f32_e32 v146, v142, v4
	v_mul_f32_e32 v4, v7, v11
	v_mul_f32_e32 v147, v143, v4
	v_cvt_pk_bf16_f32 v144, v144, v145
	v_cvt_pk_bf16_f32 v145, v146, v147
	global_store_dwordx2 v[8:9], v[144:145], off offset:240
